# GQA attention loop: QK and PV MFMAs interleaved (alternating accumulators) instead of 4-long dependent chains
# baseline (speedup 1.0000x reference)
.Lgq_noload:
	v_exp_f32_e32 v32, v32
	v_exp_f32_e32 v33, v33
	v_exp_f32_e32 v34, v34
	v_exp_f32_e32 v35, v35
	s_waitcnt lgkmcnt(7)
	v_mfma_f32_32x32x16_bf16 v[48:63], v[112:115], v[76:79], 0
	v_exp_f32_e32 v36, v36
	v_exp_f32_e32 v37, v37
	v_add_f32_e32 v246, v32, v246
	v_add_f32_e32 v247, v33, v247
	v_cvt_pk_bf16_f32 v238, v32, v33
	v_mfma_f32_32x32x16_bf16 v[0:15], v[144:147], v[200:203], v[0:15]
	ds_read_b128 v[144:147], v172
	v_exp_f32_e32 v38, v38
	v_exp_f32_e32 v39, v39
	v_add_f32_e32 v248, v34, v248
	v_add_f32_e32 v249, v35, v249
	v_cvt_pk_bf16_f32 v239, v34, v35
	s_waitcnt lgkmcnt(7)
	v_mfma_f32_32x32x16_bf16 v[48:63], v[116:119], v[72:75], v[48:63]
	v_exp_f32_e32 v40, v40
	v_exp_f32_e32 v41, v41
	v_add_f32_e32 v246, v36, v246
	v_add_f32_e32 v247, v37, v247
	v_cvt_pk_bf16_f32 v240, v36, v37
	v_mfma_f32_32x32x16_bf16 v[16:31], v[164:167], v[200:203], v[16:31]
	ds_read_b128 v[164:167], v172 offset:4608
	v_exp_f32_e32 v42, v42
	v_exp_f32_e32 v43, v43
	v_add_f32_e32 v248, v38, v248
	v_add_f32_e32 v249, v39, v249
	v_cvt_pk_bf16_f32 v241, v38, v39
	s_waitcnt lgkmcnt(7)
	v_mfma_f32_32x32x16_bf16 v[48:63], v[120:123], v[68:71], v[48:63]
	v_exp_f32_e32 v44, v44
	v_exp_f32_e32 v45, v45
	v_add_f32_e32 v246, v40, v246
	v_add_f32_e32 v247, v41, v247
	v_cvt_pk_bf16_f32 v242, v40, v41
	v_mfma_f32_32x32x16_bf16 v[0:15], v[148:151], v[204:207], v[0:15]
	ds_read_b128 v[148:151], v172 offset:32
	v_exp_f32_e32 v46, v46
	v_exp_f32_e32 v47, v47
	v_add_f32_e32 v248, v42, v248
	v_add_f32_e32 v249, v43, v249
	v_cvt_pk_bf16_f32 v243, v42, v43
	s_waitcnt lgkmcnt(7)
	v_mfma_f32_32x32x16_bf16 v[48:63], v[124:127], v[64:67], v[48:63]
	v_add_f32_e32 v246, v44, v246
	v_add_f32_e32 v247, v45, v247
	v_cvt_pk_bf16_f32 v244, v44, v45
	v_add_f32_e32 v248, v46, v248
	v_add_f32_e32 v249, v47, v249
	v_mfma_f32_32x32x16_bf16 v[16:31], v[168:171], v[204:207], v[16:31]
	ds_read_b128 v[168:171], v172 offset:4640
	v_cvt_pk_bf16_f32 v245, v46, v47
	s_waitcnt lgkmcnt(7)
	v_mfma_f32_32x32x16_bf16 v[32:47], v[128:131], v[76:79], 0
	s_nop 1
	v_exp_f32_e32 v48, v48
	v_exp_f32_e32 v49, v49
	v_exp_f32_e32 v50, v50
	v_exp_f32_e32 v51, v51
	v_exp_f32_e32 v52, v52
	v_add_f32_e32 v246, v48, v246
	v_add_f32_e32 v247, v49, v247
	v_cvt_pk_bf16_f32 v200, v48, v49
	v_mfma_f32_32x32x16_bf16 v[0:15], v[152:155], v[238:241], v[0:15]
	ds_read_b128 v[152:155], v172 offset:64
	v_exp_f32_e32 v53, v53
	v_exp_f32_e32 v54, v54
	v_add_f32_e32 v248, v50, v248
	v_add_f32_e32 v249, v51, v249
	v_cvt_pk_bf16_f32 v201, v50, v51
	s_waitcnt lgkmcnt(7)
	v_mfma_f32_32x32x16_bf16 v[32:47], v[132:135], v[72:75], v[32:47]
	v_exp_f32_e32 v55, v55
	v_exp_f32_e32 v56, v56
	v_add_f32_e32 v246, v52, v246
	v_add_f32_e32 v247, v53, v247
	v_cvt_pk_bf16_f32 v202, v52, v53
	v_mfma_f32_32x32x16_bf16 v[16:31], v[184:187], v[238:241], v[16:31]
	ds_read_b128 v[184:187], v172 offset:4672
	v_exp_f32_e32 v57, v57
	v_exp_f32_e32 v58, v58
	v_add_f32_e32 v248, v54, v248
	v_add_f32_e32 v249, v55, v249
	v_cvt_pk_bf16_f32 v203, v54, v55
	s_waitcnt lgkmcnt(7)
	v_mfma_f32_32x32x16_bf16 v[32:47], v[136:139], v[68:71], v[32:47]
	v_exp_f32_e32 v59, v59
	v_exp_f32_e32 v60, v60
	v_add_f32_e32 v246, v56, v246
	v_add_f32_e32 v247, v57, v247
	v_cvt_pk_bf16_f32 v204, v56, v57
	v_mfma_f32_32x32x16_bf16 v[0:15], v[160:163], v[242:245], v[0:15]
	ds_read_b128 v[160:163], v172 offset:96
	v_exp_f32_e32 v61, v61
	v_exp_f32_e32 v62, v62
	v_add_f32_e32 v248, v58, v248
	v_add_f32_e32 v249, v59, v249
	v_cvt_pk_bf16_f32 v205, v58, v59
	s_waitcnt lgkmcnt(7)
	v_mfma_f32_32x32x16_bf16 v[32:47], v[140:143], v[64:67], v[32:47]
	v_exp_f32_e32 v63, v63
	v_add_f32_e32 v246, v60, v246
	v_add_f32_e32 v247, v61, v247
	v_cvt_pk_bf16_f32 v206, v60, v61
	v_add_f32_e32 v248, v62, v248
	v_mfma_f32_32x32x16_bf16 v[16:31], v[196:199], v[242:245], v[16:31]
	ds_read_b128 v[196:199], v172 offset:4704
	v_add_f32_e32 v249, v63, v249
	v_cvt_pk_bf16_f32 v207, v62, v63
	s_cmpk_eq_i32 s0, 0x10c0
	s_cbranch_scc1 .Lgq_nostore
	s_and_b32 s1, s0, 64
	s_xor_b32 s1, s1, 64
	s_mul_i32 s6, s1, 0x90
	v_add_u32_e32 v111, s6, v188
	v_add_u32_e32 v250, s6, v181
	v_add_u32_e32 v251, s6, v189
	v_add_u32_e32 v237, s6, v183
	s_waitcnt vmcnt(3)
	ds_write_b128 v111, v[92:95]
	s_waitcnt vmcnt(2)
	ds_write2_b64 v250, v[84:85], v[86:87] offset1:2
	s_waitcnt vmcnt(1)
	ds_write_b128 v251, v[88:91]
	s_waitcnt vmcnt(0)
	ds_write2_b64 v237, v[80:81], v[82:83] offset1:2
